# fuse out-proj GEMM -> LayerNorm (ph5/11/15/20): 8-block M-tile team sync (sc1 stores + atomic counter + inv) replaces 4 grid barriers; LN rows remapped to the team
# speedup vs baseline: 1.0261x; 1.0107x over previous
.LBB0_492:
	s_load_dword s66, s[0:1], 0x468
	s_waitcnt lgkmcnt(0)
	s_cmpk_lg_u32 s66, 0x200
	s_cbranch_scc1 FUSE5_ORIG
	s_cmp_lt_i32 s23, 7
	s_cbranch_scc1 FUSE5_ORIG
	s_waitcnt vmcnt(0)
	s_barrier
	v_bfe_u32 v5, v0, 6, 2
	s_and_b32 s73, s2, 0x1ff
	s_nop 1
	v_readfirstlane_b32 s67, v5
	s_cmp_lg_u32 s67, 0
	s_cbranch_scc1 FUSE5_WAIT
	s_and_b32 s67, s73, 63
	s_lshl_b32 s68, s67, 6
	s_and_b32 s69, s67, 32
	s_lshl_b32 s69, s69, 6
	s_add_u32 s68, s68, s69
	s_add_u32 s68, s68, 0x1c00
	v_mov_b32_e32 v2, s68
	v_mov_b32_e32 v3, 1
	s_mov_b64 s[70:71], exec
	s_mov_b64 exec, 1
	s_mov_b32 s74, 0
	global_atomic_add v2, v3, s[20:21]
FUSE5_SPIN:
	global_load_dword v4, v2, s[20:21] sc1
	s_waitcnt vmcnt(0)
	v_readfirstlane_b32 s69, v4
	s_cmp_ge_u32 s69, 8
	s_cbranch_scc1 FUSE5_GOT
	s_add_i32 s74, s74, 1
	s_cmp_gt_u32 s74, 0x20000
	s_cbranch_scc1 FUSE5_GOT
	s_sleep 1
	s_branch FUSE5_SPIN
FUSE5_GOT:
	s_mov_b64 exec, s[70:71]
	buffer_inv sc1
	s_waitcnt vmcnt(0)
FUSE5_WAIT:
	s_barrier
	s_and_b32 s67, s73, 63
	s_lshr_b32 s68, s73, 6
	s_mul_i32 s67, s67, 48
	s_mul_i32 s68, s68, 6
	s_add_i32 s72, s67, s68
	s_lshl_b32 s35, s72, 2
	s_add_i32 s35, s35, 24
	s_mov_b32 s3, 1
	s_branch FUSE5_LN
FUSE5_ORIG:
	s_cmp_lt_i32 s23, 7
	s_cbranch_scc1 .LBB0_545
	s_waitcnt vmcnt(0)
	v_and_b32_e32 v3, 0x3ff, v0
	v_cmp_eq_u32_e32 vcc, 0, v3
	v_mov_b32_e32 v2, v146
	v_mov_b32_e32 v4, v148
	s_waitcnt vmcnt(0) lgkmcnt(0)
	s_barrier
	s_and_saveexec_b64 s[4:5], vcc
	s_cbranch_execz .LBB0_542
	v_cmp_eq_u32_e32 vcc, 0, v148
	v_mov_b32_e32 v2, v146
	v_mov_b32_e32 v4, v148
	s_waitcnt vmcnt(0) expcnt(0) lgkmcnt(0)
	s_and_saveexec_b64 s[6:7], vcc
	s_cbranch_execz .LBB0_509
	s_load_dwordx2 s[12:13], s[0:1], 0x468
	s_load_dword s3, s[0:1], 0x470
	s_add_u32 s8, s20, 0x1000
	s_addc_u32 s9, s21, 0
	s_add_u32 s10, s20, 0x1100
	s_waitcnt lgkmcnt(0)
	s_mul_i32 s11, s13, s12
	s_mul_i32 s3, s11, s3
	s_addc_u32 s11, s21, 0
	s_add_u32 s12, s20, 0x1200
	s_addc_u32 s13, s21, 0
	s_add_u32 s14, s20, 0x1300
	s_addc_u32 s15, s21, 0
	s_mov_b32 s26, 1
	v_mov_b32_e32 v19, 0
	s_branch .LBB0_497

.LBB0_545:
	s_cmp_gt_i32 s22, 6
	s_cselect_b64 s[4:5], -1, 0
	s_cmp_lt_i32 s23, 7
	s_cselect_b64 s[6:7], -1, 0
	s_or_b64 s[4:5], s[4:5], s[6:7]
	s_and_b64 vcc, exec, s[4:5]
	s_cbranch_vccnz .LBB0_622
	s_load_dword s3, s[0:1], 0x468
	s_mov_b32 s72, s2
	s_movk_i32 s35, 0x3000
	s_waitcnt lgkmcnt(0)
FUSE5_LN:
	s_add_u32 s10, s0, 0x468
	v_lshl_or_b32 v10, s72, 2, v1
	v_and_b32_e32 v39, 0x3ff, v0
	s_addc_u32 s11, s1, 0
	v_cmp_gt_i32_e32 vcc, s35, v10
	s_and_saveexec_b64 s[24:25], vcc
	s_cbranch_execz .LBB0_569
	v_mbcnt_lo_u32_b32 v3, -1, 0
	v_mbcnt_hi_u32_b32 v3, -1, v3
	v_and_b32_e32 v4, 64, v3
	v_add_u32_e32 v4, 64, v4
	v_xor_b32_e32 v5, 32, v3
	v_cmp_lt_i32_e32 vcc, v5, v4
	s_load_dwordx4 s[4:7], s[0:1], 0x50
	s_load_dwordx4 s[12:15], s[0:1], 0x0
	v_cndmask_b32_e32 v5, v3, v5, vcc
	v_lshlrev_b32_e32 v96, 2, v5
	v_xor_b32_e32 v5, 16, v3
	v_cmp_lt_i32_e32 vcc, v5, v4
	v_lshlrev_b32_e32 v2, 2, v39
	v_and_b32_e32 v2, 0xfc, v2
	v_cndmask_b32_e32 v5, v3, v5, vcc
	v_lshlrev_b32_e32 v97, 2, v5
	v_xor_b32_e32 v5, 8, v3
	v_cmp_lt_i32_e32 vcc, v5, v4
	v_mov_b32_e32 v13, 0
	v_lshlrev_b32_e32 v12, 2, v2
	v_cndmask_b32_e32 v5, v3, v5, vcc
	v_lshlrev_b32_e32 v98, 2, v5
	v_xor_b32_e32 v5, 4, v3
	v_cmp_lt_i32_e32 vcc, v5, v4
	s_waitcnt lgkmcnt(0)
	v_lshl_add_u64 v[14:15], s[4:5], 0, v[12:13]
	v_lshl_add_u64 v[16:17], s[6:7], 0, v[12:13]
	v_cndmask_b32_e32 v5, v3, v5, vcc
	v_lshlrev_b32_e32 v99, 2, v5
	v_xor_b32_e32 v5, 2, v3
	v_cmp_lt_i32_e32 vcc, v5, v4
	s_load_dwordx2 s[4:5], s[0:1], 0xa0
	s_load_dwordx4 s[16:19], s[0:1], 0x88
	v_cndmask_b32_e32 v5, v3, v5, vcc
	s_load_dwordx2 s[6:7], s[0:1], 0xb0
	s_lshl_b32 s37, s3, 2
	v_lshlrev_b32_e32 v100, 2, v5
	v_xor_b32_e32 v5, 1, v3
	v_cmp_lt_i32_e32 vcc, v5, v4
	v_add_u32_e32 v26, s37, v10
	s_lshl_b32 s26, s3, 3
	v_cndmask_b32_e32 v3, v3, v5, vcc
	v_ashrrev_i32_e32 v11, 31, v10
	v_ashrrev_i32_e32 v27, 31, v26
	v_lshlrev_b32_e32 v101, 2, v3
	v_or_b32_e32 v4, 0x100, v2
	v_or_b32_e32 v6, 0x200, v2
	v_or_b32_e32 v8, 0x300, v2
	v_lshlrev_b32_e32 v12, 1, v2
	v_lshlrev_b64 v[20:21], 12, v[10:11]
	s_ashr_i32 s27, s26, 31
	v_and_b32_e32 v3, 63, v39
	v_lshlrev_b64 v[32:33], 11, v[10:11]
	v_lshlrev_b64 v[28:29], 11, v[26:27]
	v_lshlrev_b32_e32 v34, 2, v2
	s_waitcnt lgkmcnt(0)
	v_lshl_add_u64 v[18:19], s[4:5], 0, v[12:13]
	v_lshl_add_u64 v[20:21], s[12:13], 0, v[20:21]
	s_lshl_b64 s[28:29], s[26:27], 12
	v_lshlrev_b32_e32 v22, 3, v3
	v_mov_b32_e32 v23, v13
	v_lshl_add_u64 v[24:25], s[4:5], 0, v[32:33]
	s_lshl_b64 s[30:31], s[26:27], 11
	v_lshl_add_u64 v[26:27], s[6:7], 0, v[28:29]
	v_lshl_add_u64 v[28:29], s[18:19], 0, v[28:29]
	v_lshl_add_u64 v[30:31], s[6:7], 0, v[32:33]
	v_lshl_add_u64 v[32:33], s[18:19], 0, v[32:33]
	s_mov_b64 s[18:19], 0
	s_movk_i32 s27, 0x1000
	s_movk_i32 s40, 0xfff
	v_mov_b32_e32 v36, v34
	v_mov_b32_e32 v37, v13
	s_mov_b32 s34, 0x3fd744fd
	s_mov_b32 s36, 0x3a800000
	v_mov_b32_e32 v38, 0x3727c5ac
	s_mov_b32 s41, 0x800000
	s_movk_i32 s42, 0xc00
	s_mov_b64 s[38:39], 0x1000
	v_lshlrev_b32_e32 v40, 2, v4
	v_lshlrev_b32_e32 v42, 2, v6
	v_lshlrev_b32_e32 v44, 2, v8
	s_add_i32 s43, s35, -1
	v_mov_b32_e32 v11, 0x4800
	v_mov_b32_e32 v102, 0x3c00
	s_branch .LBB0_549

.LBB0_1136:
	s_load_dword s66, s[0:1], 0x468
	s_waitcnt lgkmcnt(0)
	s_cmpk_lg_u32 s66, 0x200
	s_cbranch_scc1 FUSE11_ORIG
	s_cmp_lt_i32 s23, 13
	s_cbranch_scc1 FUSE11_ORIG
	s_waitcnt vmcnt(0)
	s_barrier
	v_bfe_u32 v5, v0, 6, 2
	s_and_b32 s73, s2, 0x1ff
	s_nop 1
	v_readfirstlane_b32 s67, v5
	s_cmp_lg_u32 s67, 0
	s_cbranch_scc1 FUSE11_WAIT
	s_and_b32 s67, s73, 63
	s_lshl_b32 s68, s67, 6
	s_and_b32 s69, s67, 32
	s_lshl_b32 s69, s69, 6
	s_add_u32 s68, s68, s69
	s_add_u32 s68, s68, 0x1c00
	v_mov_b32_e32 v2, s68
	v_mov_b32_e32 v3, 1
	s_mov_b64 s[70:71], exec
	s_mov_b64 exec, 1
	s_mov_b32 s74, 0
	global_atomic_add v2, v3, s[20:21]
FUSE11_SPIN:
	global_load_dword v4, v2, s[20:21] sc1
	s_waitcnt vmcnt(0)
	v_readfirstlane_b32 s69, v4
	s_cmp_ge_u32 s69, 16
	s_cbranch_scc1 FUSE11_GOT
	s_add_i32 s74, s74, 1
	s_cmp_gt_u32 s74, 0x20000
	s_cbranch_scc1 FUSE11_GOT
	s_sleep 1
	s_branch FUSE11_SPIN
FUSE11_GOT:
	s_mov_b64 exec, s[70:71]
	buffer_inv sc1
	s_waitcnt vmcnt(0)
FUSE11_WAIT:
	s_barrier
	s_and_b32 s67, s73, 63
	s_lshr_b32 s68, s73, 6
	s_mul_i32 s67, s67, 48
	s_mul_i32 s68, s68, 6
	s_add_i32 s72, s67, s68
	s_lshl_b32 s25, s72, 2
	s_add_i32 s25, s25, 24
	s_mov_b32 s3, 1
	s_branch FUSE11_LN
FUSE11_ORIG:
	s_cmp_lt_i32 s23, 13
	s_cbranch_scc1 .LBB0_1189
	s_waitcnt vmcnt(0)
	s_waitcnt vmcnt(0)
	v_and_b32_e32 v3, 0x3ff, v0
	v_cmp_eq_u32_e32 vcc, 0, v3
	v_mov_b32_e32 v2, v146
	v_mov_b32_e32 v4, v148
	s_waitcnt lgkmcnt(0)
	s_barrier
	s_and_saveexec_b64 s[4:5], vcc
	s_cbranch_execz .LBB0_1186
	v_cmp_eq_u32_e32 vcc, 0, v148
	v_mov_b32_e32 v2, v146
	v_mov_b32_e32 v4, v148
	s_waitcnt vmcnt(0) expcnt(0) lgkmcnt(0)
	s_and_saveexec_b64 s[6:7], vcc
	s_cbranch_execz .LBB0_1153
	s_load_dwordx2 s[12:13], s[0:1], 0x468
	s_load_dword s3, s[0:1], 0x470
	s_add_u32 s8, s20, 0x1000
	s_addc_u32 s9, s21, 0
	s_add_u32 s10, s20, 0x1100
	s_waitcnt lgkmcnt(0)
	s_mul_i32 s11, s13, s12
	s_mul_i32 s3, s11, s3
	s_addc_u32 s11, s21, 0
	s_add_u32 s12, s20, 0x1200
	s_addc_u32 s13, s21, 0
	s_add_u32 s14, s20, 0x1300
	s_addc_u32 s15, s21, 0
	s_mov_b32 s26, 1
	v_mov_b32_e32 v19, 0
	s_branch .LBB0_1141

.LBB0_1189:
	s_cmp_gt_i32 s22, 12
	s_cselect_b64 s[4:5], -1, 0
	s_cmp_lt_i32 s23, 13
	s_cselect_b64 s[6:7], -1, 0
	s_or_b64 s[4:5], s[4:5], s[6:7]
	s_and_b64 vcc, exec, s[4:5]
	s_cbranch_vccnz .LBB0_1262
	s_waitcnt lgkmcnt(0)
	s_load_dword s3, s[0:1], 0x468
	s_mov_b32 s72, s2
	s_movk_i32 s25, 0x3000
	s_waitcnt lgkmcnt(0)
FUSE11_LN:
	s_add_u32 s6, s0, 0x468
	v_lshl_or_b32 v10, s72, 2, v1
	v_and_b32_e32 v47, 0x3ff, v0
	s_addc_u32 s7, s1, 0
	v_cmp_gt_i32_e32 vcc, s25, v10
	s_and_saveexec_b64 s[12:13], vcc
	s_cbranch_execz .LBB0_1209
	s_waitcnt vmcnt(0)
	v_mbcnt_lo_u32_b32 v3, -1, 0
	v_mbcnt_hi_u32_b32 v3, -1, v3
	v_and_b32_e32 v4, 64, v3
	v_add_u32_e32 v4, 64, v4
	v_xor_b32_e32 v5, 32, v3
	v_cmp_lt_i32_e32 vcc, v5, v4
	s_load_dwordx4 s[16:19], s[0:1], 0x50
	s_load_dwordx4 s[8:11], s[0:1], 0x88
	v_cndmask_b32_e32 v5, v3, v5, vcc
	v_lshlrev_b32_e32 v106, 2, v5
	v_xor_b32_e32 v5, 16, v3
	v_cmp_lt_i32_e32 vcc, v5, v4
	s_waitcnt lgkmcnt(0)
	s_lshl_b32 s27, s3, 2
	s_add_u32 s4, s18, 0x1000
	v_cndmask_b32_e32 v5, v3, v5, vcc
	v_lshlrev_b32_e32 v107, 2, v5
	v_xor_b32_e32 v5, 8, v3
	v_cmp_lt_i32_e32 vcc, v5, v4
	s_addc_u32 s5, s19, 0
	v_lshlrev_b32_e32 v2, 2, v47
	v_cndmask_b32_e32 v5, v3, v5, vcc
	v_lshlrev_b32_e32 v108, 2, v5
	v_xor_b32_e32 v5, 4, v3
	v_cmp_lt_i32_e32 vcc, v5, v4
	s_add_u32 s18, s16, 0x1000
	v_and_b32_e32 v2, 0xfc, v2
	v_cndmask_b32_e32 v5, v3, v5, vcc
	v_lshlrev_b32_e32 v109, 2, v5
	v_xor_b32_e32 v5, 2, v3
	v_cmp_lt_i32_e32 vcc, v5, v4
	s_addc_u32 s19, s17, 0
	v_mov_b32_e32 v13, 0
	v_cndmask_b32_e32 v5, v3, v5, vcc
	v_lshlrev_b32_e32 v110, 2, v5
	v_xor_b32_e32 v5, 1, v3
	v_cmp_lt_i32_e32 vcc, v5, v4
	v_lshlrev_b32_e32 v12, 2, v2
	v_or_b32_e32 v4, 0x100, v2
	s_load_dwordx2 s[28:29], s[0:1], 0xa0
	s_load_dwordx2 s[30:31], s[0:1], 0xb0
	v_lshl_add_u64 v[14:15], s[18:19], 0, v[12:13]
	v_lshl_add_u64 v[16:17], s[4:5], 0, v[12:13]
	v_lshlrev_b32_e32 v12, 2, v4
	v_or_b32_e32 v6, 0x200, v2
	v_lshl_add_u64 v[18:19], s[18:19], 0, v[12:13]
	v_lshl_add_u64 v[20:21], s[4:5], 0, v[12:13]
	v_lshlrev_b32_e32 v12, 2, v6
	v_or_b32_e32 v8, 0x300, v2
	v_add_u32_e32 v38, s27, v10
	v_cndmask_b32_e32 v3, v3, v5, vcc
	s_lshl_b32 s16, s3, 3
	v_lshl_add_u64 v[22:23], s[18:19], 0, v[12:13]
	v_lshl_add_u64 v[24:25], s[4:5], 0, v[12:13]
	v_lshlrev_b32_e32 v12, 2, v8
	v_ashrrev_i32_e32 v11, 31, v10
	v_ashrrev_i32_e32 v39, 31, v38
	v_lshlrev_b32_e32 v111, 2, v3
	v_lshl_add_u64 v[26:27], s[18:19], 0, v[12:13]
	v_lshl_add_u64 v[28:29], s[4:5], 0, v[12:13]
	v_lshlrev_b32_e32 v12, 1, v2
	v_and_b32_e32 v3, 63, v47
	v_lshlrev_b64 v[44:45], 11, v[10:11]
	s_ashr_i32 s17, s16, 31
	v_lshlrev_b64 v[42:43], 11, v[38:39]
	s_mov_b64 s[14:15], 0x1000
	s_waitcnt lgkmcnt(0)
	v_lshl_add_u64 v[30:31], s[28:29], 0, v[12:13]
	v_lshl_add_u64 v[32:33], s[30:31], 0, v[12:13]
	v_lshlrev_b32_e32 v34, 3, v3
	v_mov_b32_e32 v35, v13
	v_lshl_add_u64 v[36:37], s[30:31], 0, v[44:45]
	s_lshl_b64 s[18:19], s[16:17], 11
	v_lshl_add_u64 v[38:39], s[30:31], 0, v[42:43]
	v_lshl_add_u64 v[40:41], s[28:29], 0, v[44:45]
	v_lshl_add_u64 v[42:43], s[10:11], 0, v[42:43]
	v_lshl_add_u64 v[44:45], s[10:11], 0, v[44:45]
	s_mov_b64 s[10:11], 0
	s_mov_b32 s24, 0x3fd744fd
	s_mov_b32 s26, 0x3a800000
	v_mov_b32_e32 v46, 0x3727c5ac
	s_mov_b32 s17, 0x800000
	s_movk_i32 s28, 0xc00
	s_movk_i32 s29, 0xfff
	v_lshlrev_b32_e32 v48, 2, v2
	v_lshlrev_b32_e32 v50, 2, v4
	v_lshlrev_b32_e32 v52, 2, v6
	v_lshlrev_b32_e32 v54, 2, v8
	s_add_i32 s30, s25, -1
	v_mov_b32_e32 v11, 0x8400
	v_mov_b32_e32 v112, 0x7800
	s_branch .LBB0_1193

.LBB0_1862:
	s_load_dword s66, s[0:1], 0x468
	s_waitcnt lgkmcnt(0)
	s_cmpk_lg_u32 s66, 0x200
	s_cbranch_scc1 FUSE15_ORIG
	s_cmp_lt_i32 s23, 17
	s_cbranch_scc1 FUSE15_ORIG
	s_waitcnt vmcnt(0)
	s_barrier
	v_bfe_u32 v5, v0, 6, 2
	s_and_b32 s73, s2, 0x1ff
	s_nop 1
	v_readfirstlane_b32 s67, v5
	s_cmp_lg_u32 s67, 0
	s_cbranch_scc1 FUSE15_WAIT
	s_and_b32 s67, s73, 63
	s_lshl_b32 s68, s67, 6
	s_and_b32 s69, s67, 32
	s_lshl_b32 s69, s69, 6
	s_add_u32 s68, s68, s69
	s_add_u32 s68, s68, 0x1c00
	v_mov_b32_e32 v2, s68
	v_mov_b32_e32 v3, 1
	s_mov_b64 s[70:71], exec
	s_mov_b64 exec, 1
	s_mov_b32 s74, 0
	global_atomic_add v2, v3, s[20:21]
FUSE15_SPIN:
	global_load_dword v4, v2, s[20:21] sc1
	s_waitcnt vmcnt(0)
	v_readfirstlane_b32 s69, v4
	s_cmp_ge_u32 s69, 24
	s_cbranch_scc1 FUSE15_GOT
	s_add_i32 s74, s74, 1
	s_cmp_gt_u32 s74, 0x20000
	s_cbranch_scc1 FUSE15_GOT
	s_sleep 1
	s_branch FUSE15_SPIN
FUSE15_GOT:
	s_mov_b64 exec, s[70:71]
	buffer_inv sc1
	s_waitcnt vmcnt(0)
FUSE15_WAIT:
	s_barrier
	s_and_b32 s67, s73, 63
	s_lshr_b32 s68, s73, 6
	s_mul_i32 s67, s67, 48
	s_mul_i32 s68, s68, 6
	s_add_i32 s72, s67, s68
	s_lshl_b32 s19, s72, 2
	s_add_i32 s19, s19, 24
	s_mov_b32 s3, 1
	s_branch FUSE15_LN
FUSE15_ORIG:
	s_cmp_lt_i32 s23, 17
	s_cbranch_scc1 .LBB0_1915
	s_waitcnt vmcnt(0)
	s_waitcnt vmcnt(0)
	v_and_b32_e32 v3, 0x3ff, v0
	v_cmp_eq_u32_e32 vcc, 0, v3
	v_mov_b32_e32 v2, v146
	v_mov_b32_e32 v4, v148
	s_waitcnt lgkmcnt(0)
	s_barrier
	s_and_saveexec_b64 s[4:5], vcc
	s_cbranch_execz .LBB0_1912
	v_cmp_eq_u32_e32 vcc, 0, v148
	v_mov_b32_e32 v2, v146
	v_mov_b32_e32 v4, v148
	s_waitcnt vmcnt(0) expcnt(0) lgkmcnt(0)
	s_and_saveexec_b64 s[6:7], vcc
	s_cbranch_execz .LBB0_1879
	s_load_dwordx2 s[12:13], s[0:1], 0x468
	s_load_dword s3, s[0:1], 0x470
	s_add_u32 s8, s20, 0x1000
	s_addc_u32 s9, s21, 0
	s_add_u32 s10, s20, 0x1100
	s_waitcnt lgkmcnt(0)
	s_mul_i32 s11, s13, s12
	s_mul_i32 s3, s11, s3
	s_addc_u32 s11, s21, 0
	s_add_u32 s12, s20, 0x1200
	s_addc_u32 s13, s21, 0
	s_add_u32 s14, s20, 0x1300
	s_addc_u32 s15, s21, 0
	s_mov_b32 s26, 1
	v_mov_b32_e32 v19, 0
	s_branch .LBB0_1867

.LBB0_1915:
	s_cmp_gt_i32 s22, 16
	s_cselect_b64 s[4:5], -1, 0
	s_cmp_lt_i32 s23, 17
	s_cselect_b64 s[6:7], -1, 0
	s_or_b64 s[4:5], s[4:5], s[6:7]
	s_and_b64 vcc, exec, s[4:5]
	s_cbranch_vccnz .LBB0_1988
	s_waitcnt lgkmcnt(0)
	s_load_dword s3, s[0:1], 0x468
	s_mov_b32 s72, s2
	s_movk_i32 s19, 0x3000
	s_waitcnt lgkmcnt(0)
FUSE15_LN:
	s_add_u32 s6, s0, 0x468
	v_lshl_or_b32 v10, s72, 2, v1
	v_and_b32_e32 v47, 0x3ff, v0
	s_addc_u32 s7, s1, 0
	v_cmp_gt_i32_e32 vcc, s19, v10
	s_and_saveexec_b64 s[12:13], vcc
	s_cbranch_execz .LBB0_1935
	s_waitcnt vmcnt(0)
	v_mbcnt_lo_u32_b32 v3, -1, 0
	v_mbcnt_hi_u32_b32 v3, -1, v3
	v_and_b32_e32 v4, 64, v3
	v_add_u32_e32 v4, 64, v4
	v_xor_b32_e32 v5, 32, v3
	v_cmp_lt_i32_e32 vcc, v5, v4
	s_load_dwordx4 s[28:31], s[0:1], 0x50
	s_load_dwordx4 s[8:11], s[0:1], 0x88
	v_cndmask_b32_e32 v5, v3, v5, vcc
	v_lshlrev_b32_e32 v106, 2, v5
	v_xor_b32_e32 v5, 16, v3
	v_cmp_lt_i32_e32 vcc, v5, v4
	s_waitcnt lgkmcnt(0)
	s_lshl_b32 s25, s3, 2
	s_add_u32 s4, s30, 0x2000
	v_cndmask_b32_e32 v5, v3, v5, vcc
	v_lshlrev_b32_e32 v107, 2, v5
	v_xor_b32_e32 v5, 8, v3
	v_cmp_lt_i32_e32 vcc, v5, v4
	v_lshlrev_b32_e32 v2, 2, v47
	s_addc_u32 s5, s31, 0
	v_cndmask_b32_e32 v5, v3, v5, vcc
	v_lshlrev_b32_e32 v108, 2, v5
	v_xor_b32_e32 v5, 4, v3
	v_cmp_lt_i32_e32 vcc, v5, v4
	v_and_b32_e32 v2, 0xfc, v2
	s_add_u32 s16, s28, 0x2000
	v_cndmask_b32_e32 v5, v3, v5, vcc
	v_lshlrev_b32_e32 v109, 2, v5
	v_xor_b32_e32 v5, 2, v3
	v_cmp_lt_i32_e32 vcc, v5, v4
	s_addc_u32 s17, s29, 0
	v_mov_b32_e32 v13, 0
	v_cndmask_b32_e32 v5, v3, v5, vcc
	v_lshlrev_b32_e32 v110, 2, v5
	v_xor_b32_e32 v5, 1, v3
	v_cmp_lt_i32_e32 vcc, v5, v4
	v_lshlrev_b32_e32 v12, 2, v2
	v_or_b32_e32 v4, 0x100, v2
	s_load_dwordx2 s[26:27], s[0:1], 0xa0
	s_load_dwordx2 s[28:29], s[0:1], 0xb0
	v_lshl_add_u64 v[14:15], s[16:17], 0, v[12:13]
	v_lshl_add_u64 v[16:17], s[4:5], 0, v[12:13]
	v_lshlrev_b32_e32 v12, 2, v4
	v_or_b32_e32 v6, 0x200, v2
	v_lshl_add_u64 v[18:19], s[16:17], 0, v[12:13]
	v_lshl_add_u64 v[20:21], s[4:5], 0, v[12:13]
	v_lshlrev_b32_e32 v12, 2, v6
	v_or_b32_e32 v8, 0x300, v2
	v_add_u32_e32 v38, s25, v10
	v_cndmask_b32_e32 v3, v3, v5, vcc
	s_lshl_b32 s14, s3, 3
	v_lshl_add_u64 v[22:23], s[16:17], 0, v[12:13]
	v_lshl_add_u64 v[24:25], s[4:5], 0, v[12:13]
	v_lshlrev_b32_e32 v12, 2, v8
	v_ashrrev_i32_e32 v11, 31, v10
	v_ashrrev_i32_e32 v39, 31, v38
	v_lshlrev_b32_e32 v111, 2, v3
	v_lshl_add_u64 v[26:27], s[16:17], 0, v[12:13]
	v_lshl_add_u64 v[28:29], s[4:5], 0, v[12:13]
	v_lshlrev_b32_e32 v12, 1, v2
	v_and_b32_e32 v3, 63, v47
	v_lshlrev_b64 v[44:45], 11, v[10:11]
	s_ashr_i32 s15, s14, 31
	v_lshlrev_b64 v[42:43], 11, v[38:39]
	s_waitcnt lgkmcnt(0)
	v_lshl_add_u64 v[30:31], s[26:27], 0, v[12:13]
	v_lshl_add_u64 v[32:33], s[28:29], 0, v[12:13]
	v_lshlrev_b32_e32 v34, 3, v3
	v_mov_b32_e32 v35, v13
	v_lshl_add_u64 v[36:37], s[28:29], 0, v[44:45]
	s_lshl_b64 s[16:17], s[14:15], 11
	v_lshl_add_u64 v[38:39], s[28:29], 0, v[42:43]
	v_lshl_add_u64 v[40:41], s[26:27], 0, v[44:45]
	v_lshl_add_u64 v[42:43], s[10:11], 0, v[42:43]
	v_lshl_add_u64 v[44:45], s[10:11], 0, v[44:45]
	s_mov_b64 s[10:11], 0
	s_mov_b32 s18, 0x3fd744fd
	s_mov_b32 s24, 0x3a800000
	v_mov_b32_e32 v46, 0x3727c5ac
	s_mov_b32 s15, 0x800000
	s_movk_i32 s28, 0xc00
	s_movk_i32 s29, 0xfff
	s_mov_b64 s[26:27], 0x1000
	v_lshlrev_b32_e32 v48, 2, v2
	v_lshlrev_b32_e32 v50, 2, v4
	v_lshlrev_b32_e32 v52, 2, v6
	v_lshlrev_b32_e32 v54, 2, v8
	s_add_i32 s30, s19, -1
	v_mov_b32_e32 v11, 0xc000
	v_mov_b32_e32 v112, 0xb400
	s_branch .LBB0_1919

.LBB0_2334:
	s_load_dword s66, s[0:1], 0x468
	s_waitcnt lgkmcnt(0)
	s_cmpk_lg_u32 s66, 0x200
	s_cbranch_scc1 FUSE20_ORIG
	s_cmp_lt_i32 s23, 22
	s_cbranch_scc1 FUSE20_ORIG
	s_waitcnt vmcnt(0)
	s_barrier
	v_bfe_u32 v5, v0, 6, 2
	s_and_b32 s73, s2, 0x1ff
	s_nop 1
	v_readfirstlane_b32 s67, v5
	s_cmp_lg_u32 s67, 0
	s_cbranch_scc1 FUSE20_WAIT
	s_and_b32 s67, s73, 63
	s_lshl_b32 s68, s67, 6
	s_and_b32 s69, s67, 32
	s_lshl_b32 s69, s69, 6
	s_add_u32 s68, s68, s69
	s_add_u32 s68, s68, 0x1c00
	v_mov_b32_e32 v2, s68
	v_mov_b32_e32 v3, 1
	s_mov_b64 s[70:71], exec
	s_mov_b64 exec, 1
	s_mov_b32 s74, 0
	global_atomic_add v2, v3, s[20:21]
FUSE20_SPIN:
	global_load_dword v4, v2, s[20:21] sc1
	s_waitcnt vmcnt(0)
	v_readfirstlane_b32 s69, v4
	s_cmp_ge_u32 s69, 32
	s_cbranch_scc1 FUSE20_GOT
	s_add_i32 s74, s74, 1
	s_cmp_gt_u32 s74, 0x20000
	s_cbranch_scc1 FUSE20_GOT
	s_sleep 1
	s_branch FUSE20_SPIN
FUSE20_GOT:
	s_mov_b64 exec, s[70:71]
	buffer_inv sc1
	s_waitcnt vmcnt(0)
FUSE20_WAIT:
	s_barrier
	s_and_b32 s67, s73, 63
	s_lshr_b32 s68, s73, 6
	s_mul_i32 s67, s67, 48
	s_mul_i32 s68, s68, 6
	s_add_i32 s72, s67, s68
	s_lshl_b32 s19, s72, 2
	v_add_u32_e32 v150, s19, v5
	s_add_i32 s19, s19, 24
	s_mov_b32 s17, 1
	s_mov_b64 s[6:7], 0
	s_mov_b64 s[2:3], 0
	s_branch FUSE20_LN
FUSE20_ORIG:
	s_cmp_lt_i32 s23, 22
	s_cbranch_scc1 .LBB0_2387
	s_waitcnt vmcnt(0)
	v_and_b32_e32 v1, 0x3ff, v0
	v_cmp_eq_u32_e32 vcc, 0, v1
	s_waitcnt vmcnt(0)
	v_mov_b32_e32 v2, v146
	v_mov_b32_e32 v4, v148
	s_waitcnt lgkmcnt(0)
	s_barrier
	s_and_saveexec_b64 s[2:3], vcc
	s_cbranch_execz .LBB0_2384
	v_cmp_eq_u32_e32 vcc, 0, v148
	v_mov_b32_e32 v2, v146
	v_mov_b32_e32 v4, v148
	s_waitcnt vmcnt(0) expcnt(0) lgkmcnt(0)
	s_and_saveexec_b64 s[4:5], vcc
	s_cbranch_execz .LBB0_2351
	s_load_dwordx2 s[10:11], s[0:1], 0x468
	s_load_dword s9, s[0:1], 0x470
	s_add_u32 s6, s20, 0x1000
	s_addc_u32 s7, s21, 0
	s_add_u32 s8, s20, 0x1100
	s_waitcnt lgkmcnt(0)
	s_mul_i32 s24, s11, s10
	s_mul_i32 s24, s24, s9
	s_addc_u32 s9, s21, 0
	s_add_u32 s10, s20, 0x1200
	s_addc_u32 s11, s21, 0
	s_add_u32 s12, s20, 0x1300
	s_addc_u32 s13, s21, 0
	s_mov_b32 s25, 1
	v_mov_b32_e32 v18, 0
	s_branch .LBB0_2339

.LBB0_2387:
	s_cmp_gt_i32 s22, 21
	s_waitcnt lgkmcnt(0)
	s_cselect_b64 s[2:3], -1, 0
	s_cmp_lt_i32 s23, 22
	s_cselect_b64 s[4:5], -1, 0
	s_or_b64 s[2:3], s[2:3], s[4:5]
	s_mov_b64 s[6:7], 0
	s_and_b64 vcc, exec, s[2:3]
	s_mov_b64 s[2:3], 0
	s_cbranch_vccnz .LBB0_2449
	s_load_dword s17, s[0:1], 0x468
	s_movk_i32 s19, 0x3000
	s_waitcnt lgkmcnt(0)
FUSE20_LN:
	s_add_u32 s8, s0, 0x468
	v_and_b32_e32 v1, 0x3ff, v0
	s_addc_u32 s9, s1, 0
	v_cmp_gt_i32_e32 vcc, s19, v150
	s_and_saveexec_b64 s[10:11], vcc
	s_cbranch_execz .LBB0_2399
	s_waitcnt vmcnt(0)
	v_lshlrev_b32_e32 v2, 2, v1
	v_and_b32_e32 v10, 0xfc, v2
	v_mbcnt_lo_u32_b32 v2, -1, 0
	v_mbcnt_hi_u32_b32 v2, -1, v2
	v_and_b32_e32 v3, 64, v2
	v_add_u32_e32 v3, 64, v3
	v_xor_b32_e32 v4, 32, v2
	v_cmp_lt_i32_e32 vcc, v4, v3
	s_load_dwordx4 s[24:27], s[0:1], 0x50
	s_load_dwordx2 s[12:13], s[0:1], 0x80
	v_cndmask_b32_e32 v4, v2, v4, vcc
	v_lshlrev_b32_e32 v11, 2, v4
	v_xor_b32_e32 v4, 16, v2
	v_cmp_lt_i32_e32 vcc, v4, v3
	s_waitcnt lgkmcnt(0)
	s_lshl_b32 s22, s17, 2
	s_add_u32 s2, s26, 0x3000
	v_cndmask_b32_e32 v4, v2, v4, vcc
	v_lshlrev_b32_e32 v37, 2, v4
	v_xor_b32_e32 v4, 8, v2
	v_cmp_lt_i32_e32 vcc, v4, v3
	s_addc_u32 s3, s27, 0
	s_add_u32 s4, s24, 0x3000
	v_cndmask_b32_e32 v4, v2, v4, vcc
	v_lshlrev_b32_e32 v74, 2, v4
	v_xor_b32_e32 v4, 4, v2
	v_cmp_lt_i32_e32 vcc, v4, v3
	v_mov_b32_e32 v13, 0
	v_lshlrev_b32_e32 v12, 2, v10
	v_cndmask_b32_e32 v4, v2, v4, vcc
	v_lshlrev_b32_e32 v75, 2, v4
	v_xor_b32_e32 v4, 2, v2
	v_cmp_lt_i32_e32 vcc, v4, v3
	s_addc_u32 s5, s25, 0
	v_lshl_add_u64 v[14:15], s[4:5], 0, v[12:13]
	v_cndmask_b32_e32 v4, v2, v4, vcc
	v_lshlrev_b32_e32 v76, 2, v4
	v_xor_b32_e32 v4, 1, v2
	v_cmp_lt_i32_e32 vcc, v4, v3
	v_mov_b32_e32 v3, v13
	v_lshl_add_u64 v[16:17], s[2:3], 0, v[12:13]
	v_cndmask_b32_e32 v2, v2, v4, vcc
	v_lshlrev_b32_e32 v77, 2, v2
	v_or_b32_e32 v2, 0x400, v12
	v_lshl_add_u64 v[18:19], s[4:5], 0, v[2:3]
	v_lshl_add_u64 v[20:21], s[2:3], 0, v[2:3]
	v_or_b32_e32 v2, 0x800, v12
	v_lshl_add_u64 v[22:23], s[4:5], 0, v[2:3]
	v_lshl_add_u64 v[24:25], s[2:3], 0, v[2:3]
	v_or_b32_e32 v2, 0xc00, v12
	v_lshl_add_u64 v[26:27], s[4:5], 0, v[2:3]
	s_load_dwordx2 s[4:5], s[0:1], 0xa0
	s_load_dwordx2 s[14:15], s[0:1], 0xb0
	v_lshl_add_u64 v[28:29], s[2:3], 0, v[2:3]
	v_lshlrev_b32_e32 v2, 1, v10
	v_lshl_add_u64 v[34:35], s[12:13], 0, v[12:13]
	s_waitcnt lgkmcnt(0)
	v_lshl_add_u64 v[30:31], s[4:5], 0, v[2:3]
	v_lshl_add_u64 v[32:33], s[14:15], 0, v[2:3]
	s_mov_b64 s[14:15], 0
	s_mov_b32 s16, 0x3fd744fd
	s_mov_b32 s18, 0x3a800000
	v_mov_b32_e32 v36, 0x3727c5ac
	s_mov_b32 s24, 0x800000
	s_add_i32 s25, s19, -1
	s_branch .LBB0_2391
